# weight prep (phase 0): absorbed branch-C weight loop issues its 16 row loads per trip together instead of 128 serial load-wait-use steps per output
# speedup vs baseline: 1.0552x; 1.0073x over previous
; DI bf16_t f2bf(float f) { unsigned u = __float_as_uint(f); u += 0x7FFFu + ((u >> 16) & 1u); return (bf16_t)(u >> 16); }
; DI void convert_weights(CP c, int l, float* tile, int bid, int nb, int mask) {
;     ...
;         { const float* wb = c->in[I_WBR] + (size_t)(l * 3 + 2) * 512 * 1024; bf16_t* dst = (bf16_t*)(ws + WS_WBRC);
;           for (int o = bid * 512 + tid; o < 1024 * 256; o += nb * 512) { const int k = o >> 8, n = (o & 255) * 4, h = k >> 8, j = k & 255;
;               const float* a = wukv + (size_t)j * 1024 + h * 256 + 128; const float* b = wb + (size_t)(h * 128) * 1024 + n; f32x4 sacc = (f32x4){0.f, 0.f, 0.f, 0.f};
; #pragma unroll 16
;               for (int cc = 0; cc < 128; ++cc) sacc += *(const f32x4*)(b + (size_t)cc * 1024) * a[cc];
; #pragma unroll
;               for (int q = 0; q < 4; ++q) dst[(size_t)(n + q) * 1024 + k] = f2bf(sacc[q]); } }
.LBB0_1203:
	v_lshl_add_u64 v[14:15], v[8:9], 0, s[18:19]
	global_load_dwordx4 v[32:35], v[12:13], off offset:-60
	global_load_dwordx4 v[28:31], v[12:13], off offset:-44
	global_load_dwordx4 v[24:27], v[12:13], off offset:-28
	global_load_dwordx4 v[2:5], v[12:13], off offset:-12
	s_mov_b32 s89, 0
	s_mov_b32 s88, 0x401000
	v_lshl_add_u64 v[42:43], v[14:15], 0, s[88:89]
	global_load_dwordx4 v[124:127], v[42:43], off offset:-4096
	global_load_dwordx4 v[128:131], v[42:43], off
	s_mov_b32 s88, 0x403000
	v_lshl_add_u64 v[42:43], v[14:15], 0, s[88:89]
	global_load_dwordx4 v[132:135], v[42:43], off offset:-4096
	global_load_dwordx4 v[136:139], v[42:43], off
	s_mov_b32 s88, 0x405000
	v_lshl_add_u64 v[42:43], v[14:15], 0, s[88:89]
	global_load_dwordx4 v[140:143], v[42:43], off offset:-4096
	global_load_dwordx4 v[144:147], v[42:43], off
	s_mov_b32 s88, 0x407000
	v_lshl_add_u64 v[42:43], v[14:15], 0, s[88:89]
	global_load_dwordx4 v[148:151], v[42:43], off offset:-4096
	global_load_dwordx4 v[152:155], v[42:43], off
	s_mov_b32 s88, 0x409000
	v_lshl_add_u64 v[42:43], v[14:15], 0, s[88:89]
	global_load_dwordx4 v[172:175], v[42:43], off offset:-4096
	global_load_dwordx4 v[176:179], v[42:43], off
	s_mov_b32 s88, 0x40b000
	v_lshl_add_u64 v[42:43], v[14:15], 0, s[88:89]
	global_load_dwordx4 v[180:183], v[42:43], off offset:-4096
	global_load_dwordx4 v[184:187], v[42:43], off
	s_mov_b32 s88, 0x40d000
	v_lshl_add_u64 v[42:43], v[14:15], 0, s[88:89]
	global_load_dwordx4 v[212:215], v[42:43], off offset:-4096
	global_load_dwordx4 v[216:219], v[42:43], off
	s_mov_b32 s88, 0x40f000
	v_lshl_add_u64 v[42:43], v[14:15], 0, s[88:89]
	global_load_dwordx4 v[220:223], v[42:43], off offset:-4096
	global_load_dwordx4 v[224:227], v[42:43], off
	s_add_u32 s18, s18, 0x10000
	s_addc_u32 s19, s19, 0
	v_lshl_add_u64 v[12:13], v[12:13], 0, 64
	s_waitcnt vmcnt(15)
	v_fmac_f32_e32 v18, v124, v32
	v_fmac_f32_e32 v19, v125, v32
	v_fmac_f32_e32 v16, v126, v32
	v_fmac_f32_e32 v17, v127, v32
	s_waitcnt vmcnt(14)
	v_fmac_f32_e32 v18, v128, v33
	v_fmac_f32_e32 v19, v129, v33
	v_fmac_f32_e32 v16, v130, v33
	v_fmac_f32_e32 v17, v131, v33
	s_waitcnt vmcnt(13)
	v_fmac_f32_e32 v18, v132, v34
	v_fmac_f32_e32 v19, v133, v34
	v_fmac_f32_e32 v16, v134, v34
	v_fmac_f32_e32 v17, v135, v34
	s_waitcnt vmcnt(12)
	v_fmac_f32_e32 v18, v136, v35
	v_fmac_f32_e32 v19, v137, v35
	v_fmac_f32_e32 v16, v138, v35
	v_fmac_f32_e32 v17, v139, v35
	s_waitcnt vmcnt(11)
	v_fmac_f32_e32 v18, v140, v28
	v_fmac_f32_e32 v19, v141, v28
	v_fmac_f32_e32 v16, v142, v28
	v_fmac_f32_e32 v17, v143, v28
	s_waitcnt vmcnt(10)
	v_fmac_f32_e32 v18, v144, v29
	v_fmac_f32_e32 v19, v145, v29
	v_fmac_f32_e32 v16, v146, v29
	v_fmac_f32_e32 v17, v147, v29
	s_waitcnt vmcnt(9)
	v_fmac_f32_e32 v18, v148, v30
	v_fmac_f32_e32 v19, v149, v30
	v_fmac_f32_e32 v16, v150, v30
	v_fmac_f32_e32 v17, v151, v30
	s_waitcnt vmcnt(8)
	v_fmac_f32_e32 v18, v152, v31
	v_fmac_f32_e32 v19, v153, v31
	v_fmac_f32_e32 v16, v154, v31
	v_fmac_f32_e32 v17, v155, v31
	s_waitcnt vmcnt(7)
	v_fmac_f32_e32 v18, v172, v24
	v_fmac_f32_e32 v19, v173, v24
	v_fmac_f32_e32 v16, v174, v24
	v_fmac_f32_e32 v17, v175, v24
	s_waitcnt vmcnt(6)
	v_fmac_f32_e32 v18, v176, v25
	v_fmac_f32_e32 v19, v177, v25
	v_fmac_f32_e32 v16, v178, v25
	v_fmac_f32_e32 v17, v179, v25
	s_waitcnt vmcnt(5)
	v_fmac_f32_e32 v18, v180, v26
	v_fmac_f32_e32 v19, v181, v26
	v_fmac_f32_e32 v16, v182, v26
	v_fmac_f32_e32 v17, v183, v26
	s_waitcnt vmcnt(4)
	v_fmac_f32_e32 v18, v184, v27
	v_fmac_f32_e32 v19, v185, v27
	v_fmac_f32_e32 v16, v186, v27
	v_fmac_f32_e32 v17, v187, v27
	s_waitcnt vmcnt(3)
	v_fmac_f32_e32 v18, v212, v2
	v_fmac_f32_e32 v19, v213, v2
	v_fmac_f32_e32 v16, v214, v2
	v_fmac_f32_e32 v17, v215, v2
	s_waitcnt vmcnt(2)
	v_fmac_f32_e32 v18, v216, v3
	v_fmac_f32_e32 v19, v217, v3
	v_fmac_f32_e32 v16, v218, v3
	v_fmac_f32_e32 v17, v219, v3
	s_waitcnt vmcnt(1)
	v_fmac_f32_e32 v18, v220, v4
	v_fmac_f32_e32 v19, v221, v4
	v_fmac_f32_e32 v16, v222, v4
	v_fmac_f32_e32 v17, v223, v4
	s_waitcnt vmcnt(0)
	v_fmac_f32_e32 v18, v224, v5
	v_fmac_f32_e32 v19, v225, v5
	v_fmac_f32_e32 v16, v226, v5
	v_fmac_f32_e32 v17, v227, v5
	s_cmp_eq_u32 s18, 0x80000
	s_cbranch_scc0 .LBB0_1203
	v_bfe_u32 v0, v18, 16, 1
	v_ashrrev_i32_e32 v7, 31, v6
	v_add3_u32 v4, v18, v0, s35
	v_lshlrev_b32_e32 v0, 13, v10
	v_lshl_add_u64 v[2:3], v[6:7], 1, s[12:13]
	v_and_b32_e32 v0, 0x1fe000, v0
	v_lshl_add_u64 v[2:3], v[2:3], 0, v[0:1]
	v_bfe_u32 v0, v19, 16, 1
	v_add3_u32 v0, v19, v0, s35
	global_store_short_d16_hi v[2:3], v4, off
	global_store_short_d16_hi v[2:3], v0, off offset:2048
	v_bfe_u32 v0, v16, 16, 1
	v_add_co_u32_e32 v2, vcc, 0x1000, v2
	v_add3_u32 v0, v16, v0, s35
	s_nop 0
	v_addc_co_u32_e32 v3, vcc, 0, v3, vcc
	v_add_u32_e32 v10, s82, v10
	global_store_short_d16_hi v[2:3], v0, off
	v_bfe_u32 v0, v17, 16, 1
	v_cmp_lt_i32_e32 vcc, s38, v10
	v_readlane_b32 s14, v252, 45
	v_add3_u32 v0, v17, v0, s35
	s_or_b64 s[16:17], vcc, s[16:17]
	v_add_u32_e32 v11, s14, v11
	global_store_short_d16_hi v[2:3], v0, off offset:2048
	s_andn2_b64 exec, exec, s[16:17]
	s_cbranch_execnz .LBB0_1202
